# DSA scoring loop: redundant canonicalising v_max(x,x) before relu removed (16 of 53 VALU per 32-key tile)
# baseline (speedup 1.0000x reference)
;     ...
;           for (int j = 0; j < 4; ++j) {
;               const int T = wid + 8 * (i0 + j);
;               if (T < ntile32) {
;                   const int key = T * 32 + c32;
;                   f32x16 a;
; #pragma unroll
;                   for (int r = 0; r < 16; ++r) a[r] = 0.f;
; #pragma unroll
;                   for (int ks = 0; ks < 4; ++ks) a = __builtin_amdgcn_mfma_f32_32x32x16_bf16(qa[ks], kk[j][ks], a, 0, 0, 0);
; #pragma unroll
;                   for (int g4 = 0; g4 < 4; ++g4) { float s = 0.f;
; #pragma unroll
;                       for (int hh = 0; hh < 4; ++hh) s = fmaf(wv[4 * g4 + hh], fmaxf(a[4 * g4 + hh], 0.f), s);
;                       sc[(2 * g4 + hi) * 4096 + key] = s; }
.LBB0_186:
	s_waitcnt vmcnt(19)
	v_mfma_f32_32x32x16_bf16 v[2:17], v[30:33], v[46:49], 0
	s_waitcnt vmcnt(18)
	v_mfma_f32_32x32x16_bf16 v[2:17], v[22:25], v[42:45], v[2:17]
	s_waitcnt vmcnt(17)
	v_mfma_f32_32x32x16_bf16 v[2:17], v[18:21], v[38:41], v[2:17]
	s_waitcnt vmcnt(16)
	v_mfma_f32_32x32x16_bf16 v[2:17], v[26:29], v[34:37], v[2:17]
	s_nop 11
	v_max_f32_e32 v2, 0, v2
	v_max_f32_e32 v6, 0, v6
	v_max_f32_e32 v3, 0, v3
	v_max_f32_e32 v7, 0, v7
	v_fma_f32 v2, v175, v2, 0
	v_fma_f32 v6, v179, v6, 0
	v_max_f32_e32 v4, 0, v4
	v_max_f32_e32 v8, 0, v8
	v_max_f32_e32 v10, 0, v10
	v_fmac_f32_e32 v2, v176, v3
	v_fmac_f32_e32 v6, v181, v7
	v_max_f32_e32 v5, 0, v5
	v_max_f32_e32 v9, 0, v9
	v_max_f32_e32 v11, 0, v11
	v_fma_f32 v10, v184, v10, 0
	v_fmac_f32_e32 v2, v177, v4
	v_fmac_f32_e32 v6, v182, v8
	v_max_f32_e32 v12, 0, v12
	v_fmac_f32_e32 v10, v185, v11
	v_fmac_f32_e32 v2, v178, v5
	v_fmac_f32_e32 v6, v183, v9
	v_fmac_f32_e32 v10, v186, v12
	ds_write2st64_b32 v0, v2, v6 offset0:12 offset1:140
	v_max_f32_e32 v2, 0, v13
	v_fmac_f32_e32 v10, v187, v2
	v_add_u32_e32 v2, 0x10c00, v0
	ds_write_b32 v2, v10
	v_max_f32_e32 v2, 0, v14
	v_fma_f32 v2, v188, v2, 0
	v_max_f32_e32 v3, 0, v15
	v_fmac_f32_e32 v2, v189, v3
	v_max_f32_e32 v3, 0, v16
	v_fmac_f32_e32 v2, v190, v3
	v_max_f32_e32 v3, 0, v17
	v_fmac_f32_e32 v2, v191, v3
	v_add_u32_e32 v3, 0x18c00, v0
	ds_write_b32 v3, v2

;     ...
;           for (int j = 0; j < 4; ++j) {
;               const int T = wid + 8 * (i0 + j);
;               if (T < ntile32) {
;                   const int key = T * 32 + c32;
;                   f32x16 a;
; #pragma unroll
;                   for (int r = 0; r < 16; ++r) a[r] = 0.f;
; #pragma unroll
;                   for (int ks = 0; ks < 4; ++ks) a = __builtin_amdgcn_mfma_f32_32x32x16_bf16(qa[ks], kk[j][ks], a, 0, 0, 0);
; #pragma unroll
;                   for (int g4 = 0; g4 < 4; ++g4) { float s = 0.f;
; #pragma unroll
;                       for (int hh = 0; hh < 4; ++hh) s = fmaf(wv[4 * g4 + hh], fmaxf(a[4 * g4 + hh], 0.f), s);
;                       sc[(2 * g4 + hi) * 4096 + key] = s; }
.LBB0_191:
	s_waitcnt vmcnt(16)
	v_mfma_f32_32x32x16_bf16 v[2:17], v[30:33], v[126:129], 0
	v_mfma_f32_32x32x16_bf16 v[2:17], v[22:25], v[122:125], v[2:17]
	v_mfma_f32_32x32x16_bf16 v[2:17], v[18:21], v[118:121], v[2:17]
	v_mfma_f32_32x32x16_bf16 v[2:17], v[26:29], v[114:117], v[2:17]
	s_nop 11
	v_max_f32_e32 v2, 0, v2
	v_max_f32_e32 v6, 0, v6
	v_max_f32_e32 v3, 0, v3
	v_max_f32_e32 v7, 0, v7
	v_fma_f32 v2, v175, v2, 0
	v_fma_f32 v6, v179, v6, 0
	v_max_f32_e32 v4, 0, v4
	v_max_f32_e32 v8, 0, v8
	v_max_f32_e32 v10, 0, v10
	v_fmac_f32_e32 v2, v176, v3
	v_fmac_f32_e32 v6, v181, v7
	v_max_f32_e32 v5, 0, v5
	v_max_f32_e32 v9, 0, v9
	v_max_f32_e32 v11, 0, v11
	v_fma_f32 v10, v184, v10, 0
	v_fmac_f32_e32 v2, v177, v4
	v_fmac_f32_e32 v6, v182, v8
	v_max_f32_e32 v12, 0, v12
	v_fmac_f32_e32 v10, v185, v11
	v_fmac_f32_e32 v2, v178, v5
	v_fmac_f32_e32 v6, v183, v9
	v_fmac_f32_e32 v10, v186, v12
	ds_write2st64_b32 v0, v2, v6 offset1:128
	v_max_f32_e32 v2, 0, v13
	v_fmac_f32_e32 v10, v187, v2
	v_add_u32_e32 v2, 0x10000, v0
	ds_write_b32 v2, v10
	v_max_f32_e32 v2, 0, v14
	v_fma_f32 v2, v188, v2, 0
	v_max_f32_e32 v3, 0, v15
	v_fmac_f32_e32 v2, v189, v3
	v_max_f32_e32 v3, 0, v16
	v_fmac_f32_e32 v2, v190, v3
	v_max_f32_e32 v3, 0, v17
	v_fmac_f32_e32 v2, v191, v3
	v_add_u32_e32 v3, 0x18000, v0
	ds_write_b32 v3, v2
	s_add_i32 s27, s22, 0xffffffb0
	s_cmp_ge_i32 s27, s0
	s_cbranch_scc1 .LBB0_184
.LBB0_192:
	s_waitcnt vmcnt(20)
	v_mfma_f32_32x32x16_bf16 v[2:17], v[30:33], v[94:97], 0
	v_mfma_f32_32x32x16_bf16 v[2:17], v[22:25], v[90:93], v[2:17]
	v_mfma_f32_32x32x16_bf16 v[2:17], v[18:21], v[86:89], v[2:17]
	v_mfma_f32_32x32x16_bf16 v[2:17], v[26:29], v[82:85], v[2:17]
	s_nop 11
	v_max_f32_e32 v2, 0, v2
	v_max_f32_e32 v6, 0, v6
	v_max_f32_e32 v3, 0, v3
	v_max_f32_e32 v7, 0, v7
	v_fma_f32 v2, v175, v2, 0
	v_fma_f32 v6, v179, v6, 0
	v_max_f32_e32 v4, 0, v4
	v_max_f32_e32 v8, 0, v8
	v_max_f32_e32 v10, 0, v10
	v_fmac_f32_e32 v2, v176, v3
	v_fmac_f32_e32 v6, v181, v7
	v_max_f32_e32 v5, 0, v5
	v_max_f32_e32 v9, 0, v9
	v_max_f32_e32 v11, 0, v11
	v_fma_f32 v10, v184, v10, 0
	v_fmac_f32_e32 v2, v177, v4
	v_fmac_f32_e32 v6, v182, v8
	v_max_f32_e32 v12, 0, v12
	v_fmac_f32_e32 v10, v185, v11
	v_fmac_f32_e32 v2, v178, v5
	v_fmac_f32_e32 v6, v183, v9
	v_fmac_f32_e32 v10, v186, v12
	ds_write2st64_b32 v0, v2, v6 offset0:4 offset1:132
	v_max_f32_e32 v2, 0, v13
	v_fmac_f32_e32 v10, v187, v2
	v_add_u32_e32 v2, 0x10400, v0
	ds_write_b32 v2, v10
	v_max_f32_e32 v2, 0, v14
	v_fma_f32 v2, v188, v2, 0
	v_max_f32_e32 v3, 0, v15
	v_fmac_f32_e32 v2, v189, v3
	v_max_f32_e32 v3, 0, v16
	v_fmac_f32_e32 v2, v190, v3
	v_max_f32_e32 v3, 0, v17
	v_fmac_f32_e32 v2, v191, v3
	v_add_u32_e32 v3, 0x18400, v0
	ds_write_b32 v3, v2
	s_add_i32 s27, s22, 0xffffffb8
	s_cmp_ge_i32 s27, s0
	s_cbranch_scc1 .LBB0_185
.LBB0_193:
	s_waitcnt vmcnt(23)
	v_mfma_f32_32x32x16_bf16 v[2:17], v[30:33], v[62:65], 0
	s_waitcnt vmcnt(22)
	v_mfma_f32_32x32x16_bf16 v[2:17], v[22:25], v[58:61], v[2:17]
	s_waitcnt vmcnt(21)
	v_mfma_f32_32x32x16_bf16 v[2:17], v[18:21], v[54:57], v[2:17]
	s_waitcnt vmcnt(20)
	v_mfma_f32_32x32x16_bf16 v[2:17], v[26:29], v[50:53], v[2:17]
	s_nop 11
	v_max_f32_e32 v2, 0, v2
	v_max_f32_e32 v6, 0, v6
	v_max_f32_e32 v3, 0, v3
	v_max_f32_e32 v7, 0, v7
	v_fma_f32 v2, v175, v2, 0
	v_fma_f32 v6, v179, v6, 0
	v_max_f32_e32 v4, 0, v4
	v_max_f32_e32 v8, 0, v8
	v_max_f32_e32 v10, 0, v10
	v_fmac_f32_e32 v2, v176, v3
	v_fmac_f32_e32 v6, v181, v7
	v_max_f32_e32 v5, 0, v5
	v_max_f32_e32 v9, 0, v9
	v_max_f32_e32 v11, 0, v11
	v_fma_f32 v10, v184, v10, 0
	v_fmac_f32_e32 v2, v177, v4
	v_fmac_f32_e32 v6, v182, v8
	v_max_f32_e32 v12, 0, v12
	v_fmac_f32_e32 v10, v185, v11
	v_fmac_f32_e32 v2, v178, v5
	v_fmac_f32_e32 v6, v183, v9
	v_fmac_f32_e32 v10, v186, v12
	ds_write2st64_b32 v0, v2, v6 offset0:8 offset1:136
	v_max_f32_e32 v2, 0, v13
	v_fmac_f32_e32 v10, v187, v2
	v_add_u32_e32 v2, 0x10800, v0
	ds_write_b32 v2, v10
	v_max_f32_e32 v2, 0, v14
	v_fma_f32 v2, v188, v2, 0
	v_max_f32_e32 v3, 0, v15
	v_fmac_f32_e32 v2, v189, v3
	v_max_f32_e32 v3, 0, v16
	v_fmac_f32_e32 v2, v190, v3
	v_max_f32_e32 v3, 0, v17
	v_fmac_f32_e32 v2, v191, v3
	v_add_u32_e32 v3, 0x18800, v0
	ds_write_b32 v3, v2
	s_sub_i32 s27, s22, 64
	s_cmp_ge_i32 s27, s0
	s_cbranch_scc0 .LBB0_186
	s_branch .LBB0_187
.LBB0_194:
	s_waitcnt vmcnt(31)
	v_mfma_f32_32x32x16_bf16 v[2:17], v[30:33], v[158:161], 0
	s_waitcnt vmcnt(30)
	v_mfma_f32_32x32x16_bf16 v[2:17], v[22:25], v[154:157], v[2:17]
	s_waitcnt vmcnt(29)
	v_mfma_f32_32x32x16_bf16 v[2:17], v[18:21], v[150:153], v[2:17]
	s_waitcnt vmcnt(28)
	v_mfma_f32_32x32x16_bf16 v[2:17], v[26:29], v[146:149], v[2:17]
	s_nop 11
	v_max_f32_e32 v2, 0, v2
	v_max_f32_e32 v6, 0, v6
	v_max_f32_e32 v3, 0, v3
	v_max_f32_e32 v7, 0, v7
	v_fma_f32 v2, v175, v2, 0
	v_fma_f32 v6, v179, v6, 0
	v_max_f32_e32 v4, 0, v4
	v_max_f32_e32 v8, 0, v8
	v_max_f32_e32 v10, 0, v10
	v_fmac_f32_e32 v2, v176, v3
	v_fmac_f32_e32 v6, v181, v7
	v_max_f32_e32 v5, 0, v5
	v_max_f32_e32 v9, 0, v9
	v_max_f32_e32 v11, 0, v11
	v_fma_f32 v10, v184, v10, 0
	v_fmac_f32_e32 v2, v177, v4
	v_fmac_f32_e32 v6, v182, v8
	v_max_f32_e32 v12, 0, v12
	v_fmac_f32_e32 v10, v185, v11
	v_fmac_f32_e32 v2, v178, v5
	v_fmac_f32_e32 v6, v183, v9
	v_fmac_f32_e32 v10, v186, v12
	ds_write2st64_b32 v0, v2, v6 offset0:16 offset1:144
	v_max_f32_e32 v2, 0, v13
	v_fmac_f32_e32 v10, v187, v2
	v_add_u32_e32 v2, 0x11000, v0
	ds_write_b32 v2, v10
	v_max_f32_e32 v2, 0, v14
	v_fma_f32 v2, v188, v2, 0
	v_max_f32_e32 v3, 0, v15
	v_fmac_f32_e32 v2, v189, v3
	v_max_f32_e32 v3, 0, v16
	v_fmac_f32_e32 v2, v190, v3
	v_max_f32_e32 v3, 0, v17
	v_fmac_f32_e32 v2, v191, v3
	v_add_u32_e32 v3, 0x19000, v0
	ds_write_b32 v3, v2
	s_cmp_ge_i32 s25, s0
	s_cbranch_scc1 .LBB0_189
;     ...
;           for (int j = 0; j < 4; ++j) {
;               const int T = wid + 8 * (i0 + j);
;               if (T < ntile32) {
;                   const int key = T * 32 + c32;
;                   f32x16 a;
; #pragma unroll
;                   for (int r = 0; r < 16; ++r) a[r] = 0.f;
; #pragma unroll
;                   for (int ks = 0; ks < 4; ++ks) a = __builtin_amdgcn_mfma_f32_32x32x16_bf16(qa[ks], kk[j][ks], a, 0, 0, 0);
; #pragma unroll
;                   for (int g4 = 0; g4 < 4; ++g4) { float s = 0.f;
; #pragma unroll
;                       for (int hh = 0; hh < 4; ++hh) s = fmaf(wv[4 * g4 + hh], fmaxf(a[4 * g4 + hh], 0.f), s);
;                       sc[(2 * g4 + hi) * 4096 + key] = s; }
.LBB0_195:
	s_waitcnt vmcnt(27)
	v_mfma_f32_32x32x16_bf16 v[2:17], v[30:33], v[142:145], 0
	s_waitcnt vmcnt(26)
	v_mfma_f32_32x32x16_bf16 v[2:17], v[22:25], v[138:141], v[2:17]
	s_waitcnt vmcnt(25)
	v_mfma_f32_32x32x16_bf16 v[2:17], v[18:21], v[134:137], v[2:17]
	s_waitcnt vmcnt(24)
	v_mfma_f32_32x32x16_bf16 v[2:17], v[26:29], v[130:133], v[2:17]
	s_nop 11
	v_max_f32_e32 v2, 0, v2
	v_max_f32_e32 v6, 0, v6
	v_max_f32_e32 v3, 0, v3
	v_max_f32_e32 v7, 0, v7
	v_fma_f32 v2, v175, v2, 0
	v_fma_f32 v6, v179, v6, 0
	v_max_f32_e32 v4, 0, v4
	v_max_f32_e32 v8, 0, v8
	v_max_f32_e32 v10, 0, v10
	v_fmac_f32_e32 v2, v176, v3
	v_fmac_f32_e32 v6, v181, v7
	v_max_f32_e32 v5, 0, v5
	v_max_f32_e32 v9, 0, v9
	v_max_f32_e32 v11, 0, v11
	v_fma_f32 v10, v184, v10, 0
	v_fmac_f32_e32 v2, v177, v4
	v_fmac_f32_e32 v6, v182, v8
	v_max_f32_e32 v12, 0, v12
	v_fmac_f32_e32 v10, v185, v11
	v_fmac_f32_e32 v2, v178, v5
	v_fmac_f32_e32 v6, v183, v9
	v_fmac_f32_e32 v10, v186, v12
	ds_write2st64_b32 v0, v2, v6 offset0:20 offset1:148
	v_max_f32_e32 v2, 0, v13
	v_fmac_f32_e32 v10, v187, v2
	v_add_u32_e32 v2, 0x11400, v0
	ds_write_b32 v2, v10
	v_max_f32_e32 v2, 0, v14
	v_fma_f32 v2, v188, v2, 0
	v_max_f32_e32 v3, 0, v15
	v_fmac_f32_e32 v2, v189, v3
	v_max_f32_e32 v3, 0, v16
	v_fmac_f32_e32 v2, v190, v3
	v_max_f32_e32 v3, 0, v17
	v_fmac_f32_e32 v2, v191, v3
	v_add_u32_e32 v3, 0x19400, v0
	ds_write_b32 v3, v2
	s_cmp_ge_i32 s24, s0
	s_cbranch_scc1 .LBB0_190
.LBB0_196:
	s_waitcnt vmcnt(23)
	v_mfma_f32_32x32x16_bf16 v[2:17], v[30:33], v[110:113], 0
	s_waitcnt vmcnt(22)
	v_mfma_f32_32x32x16_bf16 v[2:17], v[22:25], v[106:109], v[2:17]
	s_waitcnt vmcnt(21)
	v_mfma_f32_32x32x16_bf16 v[2:17], v[18:21], v[102:105], v[2:17]
	s_waitcnt vmcnt(20)
	v_mfma_f32_32x32x16_bf16 v[2:17], v[26:29], v[98:101], v[2:17]
	s_nop 11
	v_max_f32_e32 v2, 0, v2
	v_max_f32_e32 v6, 0, v6
	v_max_f32_e32 v3, 0, v3
	v_max_f32_e32 v7, 0, v7
	v_fma_f32 v2, v175, v2, 0
	v_fma_f32 v6, v179, v6, 0
	v_max_f32_e32 v4, 0, v4
	v_max_f32_e32 v8, 0, v8
	v_max_f32_e32 v10, 0, v10
	v_fmac_f32_e32 v2, v176, v3
	v_fmac_f32_e32 v6, v181, v7
	v_max_f32_e32 v5, 0, v5
	v_max_f32_e32 v9, 0, v9
	v_max_f32_e32 v11, 0, v11
	v_fma_f32 v10, v184, v10, 0
	v_fmac_f32_e32 v2, v177, v4
	v_fmac_f32_e32 v6, v182, v8
	v_max_f32_e32 v12, 0, v12
	v_fmac_f32_e32 v10, v185, v11
	v_fmac_f32_e32 v2, v178, v5
	v_fmac_f32_e32 v6, v183, v9
	v_fmac_f32_e32 v10, v186, v12
	ds_write2st64_b32 v0, v2, v6 offset0:24 offset1:152
	v_max_f32_e32 v2, 0, v13
	v_fmac_f32_e32 v10, v187, v2
	v_add_u32_e32 v2, 0x11800, v0
	ds_write_b32 v2, v10
	v_max_f32_e32 v2, 0, v14
	v_fma_f32 v2, v188, v2, 0
	v_max_f32_e32 v3, 0, v15
	v_fmac_f32_e32 v2, v189, v3
	v_max_f32_e32 v3, 0, v16
	v_fmac_f32_e32 v2, v190, v3
	v_max_f32_e32 v3, 0, v17
	v_fmac_f32_e32 v2, v191, v3
	v_add_u32_e32 v3, 0x19800, v0
	ds_write_b32 v3, v2
	s_cmp_ge_i32 s23, s0
	s_cbranch_scc1 .LBB0_181
.LBB0_197:
	s_waitcnt vmcnt(19)
	v_mfma_f32_32x32x16_bf16 v[2:17], v[30:33], v[78:81], 0
	s_waitcnt vmcnt(18)
	v_mfma_f32_32x32x16_bf16 v[2:17], v[22:25], v[74:77], v[2:17]
	s_waitcnt vmcnt(17)
	v_mfma_f32_32x32x16_bf16 v[2:17], v[18:21], v[70:73], v[2:17]
	s_waitcnt vmcnt(16)
	v_mfma_f32_32x32x16_bf16 v[2:17], v[26:29], v[66:69], v[2:17]
	s_nop 11
	v_max_f32_e32 v2, 0, v2
	v_max_f32_e32 v6, 0, v6
	v_max_f32_e32 v3, 0, v3
	v_max_f32_e32 v7, 0, v7
	v_fma_f32 v2, v175, v2, 0
	v_fma_f32 v6, v179, v6, 0
	v_max_f32_e32 v4, 0, v4
	v_max_f32_e32 v8, 0, v8
	v_max_f32_e32 v10, 0, v10
	v_fmac_f32_e32 v2, v176, v3
	v_fmac_f32_e32 v6, v181, v7
	v_max_f32_e32 v5, 0, v5
	v_max_f32_e32 v9, 0, v9
	v_max_f32_e32 v11, 0, v11
	v_fma_f32 v10, v184, v10, 0
	v_fmac_f32_e32 v2, v177, v4
	v_fmac_f32_e32 v6, v182, v8
	v_max_f32_e32 v12, 0, v12
	v_fmac_f32_e32 v10, v185, v11
	v_fmac_f32_e32 v2, v178, v5
	v_fmac_f32_e32 v6, v183, v9
	v_fmac_f32_e32 v10, v186, v12
	ds_write2st64_b32 v0, v2, v6 offset0:28 offset1:156
	v_max_f32_e32 v2, 0, v13
	v_fmac_f32_e32 v10, v187, v2
	v_add_u32_e32 v2, 0x11c00, v0
	ds_write_b32 v2, v10
	v_max_f32_e32 v2, 0, v14
	v_fma_f32 v2, v188, v2, 0
	v_max_f32_e32 v3, 0, v15
	v_fmac_f32_e32 v2, v189, v3
	v_max_f32_e32 v3, 0, v16
	v_fmac_f32_e32 v2, v190, v3
	v_max_f32_e32 v3, 0, v17
	v_fmac_f32_e32 v2, v191, v3
	v_add_u32_e32 v3, 0x19c00, v0
	ds_write_b32 v3, v2
	s_branch .LBB0_181
